# GEMM phase prologue de-serialised: tile-1's six LDS-DMA pieces issued before the first wait/barrier (vmcnt(2) -> vmcnt(8) after 14 pieces), four of five GEMM instantiations
# speedup vs baseline: 1.0070x; 1.0005x over previous
; #define PG8_STAGE(bufoff, gbase, voff) do { _Pragma("unroll") for (int _i = 0; _i < 2; ++_i) \
;         __builtin_amdgcn_global_load_lds((const unsigned*)((const char*)(gbase) + (voff)[_i]), (LAS unsigned*)(lds + (bufoff) + ldsw + _i * 8192), 16, 0, 0); } while (0)
; #define PG8_WAIT_V(n) asm volatile("s_waitcnt vmcnt(" #n ")" ::: "memory")
; #define PG8_BAR __builtin_amdgcn_s_barrier()
; template <class Epi>
; DI void gemm_phase(LAS unsigned char* lds, const Gemm g, const StaticOrder S, const Epi E) {
;     ...
;     PG8_STAGE(PG8_SB(0, 0), cB, voffB); PG8_STAGE(PG8_SB(0, 1), cB + hstepB, voffB); PG8_STAGE(PG8_SA(0, 0), cA, voffA); PG8_STAGE(PG8_SA(0, 1), cA + hstepA, voffA);
;     if (wr == 1) PG8_BAR;
;     PG8_WAIT_V(2); PG8_BAR;
;     PG8_STAGE(PG8_SB(1, 0), cB + kstep, voffB); PG8_STAGE(PG8_SA(1, 0), cA + kstep, voffA); PG8_STAGE(PG8_SB(1, 1), cB + hstepB + kstep, voffB);
;     PG8_WAIT_V(6); PG8_BAR;
.LBB0_276:
	s_lshl_b32 s20, s42, 5
	s_and_b32 s62, s20, 0x60
	s_lshl_b32 s61, s41, 6
	s_lshl_b32 s22, s41, 13
	s_lshl_b32 s23, s62, 7
	s_add_u32 s64, s38, 0x9cba200
	s_addc_u32 s65, s39, 0
	s_add_u32 s66, s38, 0xa0ba200
	s_addc_u32 s67, s39, 0
	s_add_i32 m0, s49, 0x18000
	v_lshl_add_u64 v[6:7], v[6:7], 0, s[94:95]
	global_load_lds_dwordx4 v[6:7], off
	v_lshl_add_u64 v[4:5], v[4:5], 0, s[94:95]
	s_add_i32 m0, s49, 0x1a000
	s_add_i32 s68, s49, 0x8000
	s_add_i32 s69, s49, 0xa000
	global_load_lds_dwordx4 v[4:5], off
	v_lshl_add_u64 v[0:1], v[0:1], 0, s[94:95]
	s_mov_b32 m0, s68
	s_add_u32 s20, s30, 0x40080
	global_load_lds_dwordx4 v[0:1], off
	v_lshl_add_u64 v[0:1], v[2:3], 0, s[94:95]
	s_mov_b32 m0, s69
	s_addc_u32 s21, s31, 0
	global_load_lds_dwordx4 v[0:1], off
	s_add_i32 m0, s49, 0x1c000
	v_lshl_add_u64 v[0:1], s[20:21], 0, v[130:131]
	global_load_lds_dwordx4 v[0:1], off
	v_lshl_add_u64 v[0:1], s[20:21], 0, v[134:135]
	s_add_i32 m0, s49, 0x1e000
	v_bfe_u32 v144, v8, 4, 2
	global_load_lds_dwordx4 v[0:1], off
	s_waitcnt vmcnt(8)
	s_barrier
	v_and_b32_e32 v141, 15, v8
	v_lshlrev_b32_e32 v0, 4, v144
	v_lshlrev_b32_e32 v1, 2, v8
	v_lshl_or_b32 v0, v141, 6, v0
	v_and_b32_e32 v1, 32, v1
	v_bitop3_b32 v2, v0, s22, v1 bitop3:0xde
	v_bitop3_b32 v145, v0, s23, v1 bitop3:0xde
	v_lshlrev_b32_e32 v0, 14, v9
	v_and_b32_e32 v0, 0xffff8000, v0
	v_lshl_add_u32 v0, v10, 11, v0
	v_and_b32_e32 v1, 1, v9
	v_lshl_or_b32 v0, v1, 6, v0
	v_lshl_add_u32 v136, v11, 1, v0
	v_lshlrev_b32_e32 v0, 14, v12
	v_and_b32_e32 v0, 0xffff8000, v0
	s_waitcnt vmcnt(6)
	v_lshl_add_u32 v0, v13, 11, v0
	v_and_b32_e32 v1, 1, v12
	s_cmpk_lt_u32 s40, 0x100
	v_lshl_or_b32 v0, v1, 6, v0
	s_cselect_b64 s[22:23], -1, 0
	v_mov_b32_e32 v137, v147
	v_lshl_add_u32 v138, v14, 1, v0
	v_mov_b32_e32 v139, v147
	s_mov_b32 s70, 0
	v_add_u32_e32 v157, 0, v2
	s_barrier
	s_branch .LBB0_279

; #define PG8_STAGE(bufoff, gbase, voff) do { _Pragma("unroll") for (int _i = 0; _i < 2; ++_i) \
;         __builtin_amdgcn_global_load_lds((const unsigned*)((const char*)(gbase) + (voff)[_i]), (LAS unsigned*)(lds + (bufoff) + ldsw + _i * 8192), 16, 0, 0); } while (0)
; #define PG8_WAIT_V(n) asm volatile("s_waitcnt vmcnt(" #n ")" ::: "memory")
; #define PG8_BAR __builtin_amdgcn_s_barrier()
; template <class Epi>
; DI void gemm_phase(LAS unsigned char* lds, const Gemm g, const StaticOrder S, const Epi E) {
;     ...
;     PG8_STAGE(PG8_SB(0, 0), cB, voffB); PG8_STAGE(PG8_SB(0, 1), cB + hstepB, voffB); PG8_STAGE(PG8_SA(0, 0), cA, voffA); PG8_STAGE(PG8_SA(0, 1), cA + hstepA, voffA);
;     if (wr == 1) PG8_BAR;
;     PG8_WAIT_V(2); PG8_BAR;
;     PG8_STAGE(PG8_SB(1, 0), cB + kstep, voffB); PG8_STAGE(PG8_SA(1, 0), cA + kstep, voffA); PG8_STAGE(PG8_SB(1, 1), cB + hstepB + kstep, voffB);
;     PG8_WAIT_V(6); PG8_BAR;
.LBB0_322:
	s_lshl_b32 s23, s41, 5
	s_and_b32 s81, s23, 0x60
	s_lshl_b32 s80, s40, 6
	s_lshl_b32 s3, s40, 13
	s_lshl_b32 s26, s81, 7
	s_add_u32 s44, s38, 0xba200
	s_addc_u32 s45, s39, 0
	s_add_u32 s46, s38, 0x2203a200
	s_addc_u32 s47, s39, 0
	s_add_u32 s48, s38, 0x2423a200
	s_addc_u32 s49, s39, 0
	s_add_u32 s50, s38, 0x4ba200
	s_addc_u32 s51, s39, 0
	s_add_i32 m0, s76, 0x18000
	v_lshl_add_u64 v[6:7], v[6:7], 0, s[94:95]
	global_load_lds_dwordx4 v[6:7], off
	v_lshl_add_u64 v[4:5], v[4:5], 0, s[94:95]
	s_add_i32 m0, s76, 0x1a000
	s_add_i32 s88, s76, 0x8000
	s_add_i32 s22, s76, 0xa000
	global_load_lds_dwordx4 v[4:5], off
	v_lshl_add_u64 v[0:1], v[0:1], 0, s[94:95]
	s_mov_b32 m0, s88
	s_add_u32 s20, s30, 0x40080
	global_load_lds_dwordx4 v[0:1], off
	v_lshl_add_u64 v[0:1], v[2:3], 0, s[94:95]
	s_mov_b32 m0, s22
	s_addc_u32 s21, s31, 0
	global_load_lds_dwordx4 v[0:1], off
	s_add_i32 m0, s76, 0x1c000
	v_lshl_add_u64 v[0:1], s[20:21], 0, v[158:159]
	global_load_lds_dwordx4 v[0:1], off
	v_lshl_add_u64 v[0:1], s[20:21], 0, v[162:163]
	s_add_i32 m0, s76, 0x1e000
	v_bfe_u32 v219, v8, 4, 2
	global_load_lds_dwordx4 v[0:1], off
	s_waitcnt vmcnt(8)
	s_barrier
	v_and_b32_e32 v157, 15, v8
	v_lshlrev_b32_e32 v0, 4, v219
	v_lshlrev_b32_e32 v1, 2, v8
	v_lshl_or_b32 v0, v157, 6, v0
	v_and_b32_e32 v1, 32, v1
	v_bitop3_b32 v2, v0, s3, v1 bitop3:0xde
	v_bitop3_b32 v220, v0, s26, v1 bitop3:0xde
	v_lshlrev_b32_e32 v0, 14, v9
	v_and_b32_e32 v0, 0xffff8000, v0
	v_lshl_add_u32 v0, v10, 11, v0
	v_and_b32_e32 v1, 1, v9
	v_lshl_or_b32 v0, v1, 6, v0
	v_lshl_add_u32 v164, v11, 1, v0
	v_lshlrev_b32_e32 v0, 14, v12
	v_and_b32_e32 v0, 0xffff8000, v0
	s_waitcnt vmcnt(6)
	v_lshl_add_u32 v0, v13, 11, v0
	v_and_b32_e32 v1, 1, v12
	s_cmpk_lt_u32 s42, 0x100
	v_lshl_or_b32 v0, v1, 6, v0
	s_cselect_b64 s[52:53], -1, 0
	s_and_b32 s13, s23, 32
	s_add_i32 s16, s80, 0xfffffc00
	v_mov_b32_e32 v165, v147
	v_lshl_add_u32 v166, v14, 1, v0
	v_mov_b32_e32 v167, v147
	s_mov_b32 s23, 0
	v_add_u32_e32 v221, 0, v2
	s_barrier
	s_branch .LBB0_325

; #define PG8_STAGE(bufoff, gbase, voff) do { _Pragma("unroll") for (int _i = 0; _i < 2; ++_i) \
;         __builtin_amdgcn_global_load_lds((const unsigned*)((const char*)(gbase) + (voff)[_i]), (LAS unsigned*)(lds + (bufoff) + ldsw + _i * 8192), 16, 0, 0); } while (0)
; #define PG8_WAIT_V(n) asm volatile("s_waitcnt vmcnt(" #n ")" ::: "memory")
; #define PG8_BAR __builtin_amdgcn_s_barrier()
; template <class Epi>
; DI void gemm_phase(LAS unsigned char* lds, const Gemm g, const StaticOrder S, const Epi E) {
;     ...
;     PG8_STAGE(PG8_SB(0, 0), cB, voffB); PG8_STAGE(PG8_SB(0, 1), cB + hstepB, voffB); PG8_STAGE(PG8_SA(0, 0), cA, voffA); PG8_STAGE(PG8_SA(0, 1), cA + hstepA, voffA);
;     if (wr == 1) PG8_BAR;
;     PG8_WAIT_V(2); PG8_BAR;
;     PG8_STAGE(PG8_SB(1, 0), cB + kstep, voffB); PG8_STAGE(PG8_SA(1, 0), cA + kstep, voffA); PG8_STAGE(PG8_SB(1, 1), cB + hstepB + kstep, voffB);
;     PG8_WAIT_V(6); PG8_BAR;
.LBB0_413:
	s_lshl_b32 s21, s41, 5
	v_readlane_b32 s0, v254, 55
	v_readlane_b32 s4, v255, 11
	s_and_b32 s72, s21, 0x60
	v_readlane_b32 s1, v254, 56
	v_readlane_b32 s5, v255, 12
	s_lshl_b32 s97, s40, 6
	s_lshl_b32 s20, s40, 13
	s_lshl_b32 s21, s72, 7
	s_and_b64 s[40:41], s[0:1], s[4:5]
	v_readlane_b32 s4, v254, 29
	s_and_b64 s[40:41], s[40:41], exec
	v_readlane_b32 s5, v254, 30
	s_cselect_b32 s56, s4, s34
	s_cselect_b32 s57, s5, s35
	s_cmp_eq_u32 s49, 7
	s_mov_b32 s1, 0x1103a200
	s_cselect_b32 s40, s1, 0x1983a200
	s_add_u32 s73, s38, s40
	s_addc_u32 s75, s39, 0
	s_add_i32 m0, s51, 0x18000
	v_lshl_add_u64 v[0:1], v[0:1], 0, s[94:95]
	global_load_lds_dwordx4 v[0:1], off
	v_lshl_add_u64 v[0:1], v[2:3], 0, s[94:95]
	s_add_i32 m0, s51, 0x1a000
	s_add_i32 s86, s51, 0x8000
	global_load_lds_dwordx4 v[0:1], off
	v_lshl_add_u64 v[0:1], v[8:9], 0, s[94:95]
	s_mov_b32 m0, s86
	s_add_i32 s87, s51, 0xa000
	global_load_lds_dwordx4 v[0:1], off
	v_lshl_add_u64 v[0:1], v[10:11], 0, s[94:95]
	s_mov_b32 m0, s87
	v_bfe_u32 v174, v12, 4, 2
	global_load_lds_dwordx4 v[0:1], off
	s_add_i32 m0, s51, 0x1c000
	v_lshl_add_u64 v[0:1], v[4:5], 0, s[94:95]
	global_load_lds_dwordx4 v[0:1], off
	v_lshl_add_u64 v[0:1], v[6:7], 0, s[94:95]
	s_add_i32 m0, s51, 0x1e000
	v_and_b32_e32 v157, 15, v12
	global_load_lds_dwordx4 v[0:1], off
	s_waitcnt vmcnt(8)
	s_barrier
	v_lshlrev_b32_e32 v0, 4, v174
	v_lshlrev_b32_e32 v1, 2, v12
	v_lshl_or_b32 v0, v157, 6, v0
	v_and_b32_e32 v1, 32, v1
	v_bitop3_b32 v2, v0, s20, v1 bitop3:0xde
	v_bitop3_b32 v175, v0, s21, v1 bitop3:0xde
	v_cvt_f32_u32_e32 v0, s76
	s_cmpk_lt_u32 s37, 0x100
	s_cselect_b64 s[60:61], -1, 0
	s_cmp_lg_u64 s[62:63], 0
	v_rcp_iflag_f32_e32 v0, v0
	s_mov_b64 s[4:5], s[62:63]
	s_cselect_b64 s[62:63], -1, 0
	s_sub_i32 s20, 0, s76
	v_mul_f32_e32 v0, 0x4f7ffffe, v0
	v_cvt_u32_f32_e32 v0, v0
	v_mov_b32_e32 v1, v147
	v_readlane_b32 s6, v254, 31
	v_readlane_b32 s7, v254, 32
	v_readfirstlane_b32 s21, v0
	v_add_u32_e32 v0, v15, v13
	v_add_lshl_u32 v0, v0, v14, 1
	s_waitcnt vmcnt(6)
	s_mul_i32 s20, s20, s21
	v_lshl_add_u64 v[138:139], s[88:89], 0, v[0:1]
	v_add_u32_e32 v0, v18, v16
	v_readlane_b32 s8, v254, 33
	v_readlane_b32 s9, v254, 34
	v_readlane_b32 s12, v254, 37
	v_readlane_b32 s18, v254, 43
	v_readlane_b32 s19, v254, 44
	s_mul_hi_u32 s20, s21, s20
	v_add_lshl_u32 v0, v0, v17, 1
	v_readlane_b32 s6, v255, 20
	s_mov_b32 s47, s46
	s_mov_b32 s58, s46
	s_mov_b32 s59, s46
	s_mov_b32 s49, s89
	s_mov_b32 s71, 0
	s_add_i32 s9, s21, s20
	v_lshl_add_u64 v[140:141], s[88:89], 0, v[0:1]
	v_add_u32_e32 v176, 0, v2
	s_mov_b64 s[18:19], s[26:27]
	s_mov_b32 s12, s65
	v_readlane_b32 s7, v255, 21
	s_mov_b32 s8, s66
	v_readlane_b32 s10, v254, 35
	v_readlane_b32 s11, v254, 36
	v_readlane_b32 s13, v254, 38
	v_readlane_b32 s14, v254, 39
	v_readlane_b32 s15, v254, 40
	v_readlane_b32 s16, v254, 41
	v_readlane_b32 s17, v254, 42
	s_barrier
	s_branch .LBB0_416

; #define PG8_STAGE(bufoff, gbase, voff) do { _Pragma("unroll") for (int _i = 0; _i < 2; ++_i) \
;         __builtin_amdgcn_global_load_lds((const unsigned*)((const char*)(gbase) + (voff)[_i]), (LAS unsigned*)(lds + (bufoff) + ldsw + _i * 8192), 16, 0, 0); } while (0)
; #define PG8_WAIT_V(n) asm volatile("s_waitcnt vmcnt(" #n ")" ::: "memory")
; #define PG8_BAR __builtin_amdgcn_s_barrier()
; template <class Epi>
; DI void gemm_phase(LAS unsigned char* lds, const Gemm g, const StaticOrder S, const Epi E) {
;     ...
;     PG8_STAGE(PG8_SB(0, 0), cB, voffB); PG8_STAGE(PG8_SB(0, 1), cB + hstepB, voffB); PG8_STAGE(PG8_SA(0, 0), cA, voffA); PG8_STAGE(PG8_SA(0, 1), cA + hstepA, voffA);
;     if (wr == 1) PG8_BAR;
;     PG8_WAIT_V(2); PG8_BAR;
;     PG8_STAGE(PG8_SB(1, 0), cB + kstep, voffB); PG8_STAGE(PG8_SA(1, 0), cA + kstep, voffA); PG8_STAGE(PG8_SB(1, 1), cB + hstepB + kstep, voffB);
;     PG8_WAIT_V(6); PG8_BAR;
.LBB0_465:
	s_lshl_b32 s21, s37, 5
	s_and_b32 s65, s21, 0x60
	s_add_i32 m0, s51, 0x18000
	v_lshl_add_u64 v[6:7], v[6:7], 0, s[94:95]
	s_lshl_b32 s64, s40, 6
	s_lshl_b32 s20, s40, 13
	s_lshl_b32 s21, s65, 7
	global_load_lds_dwordx4 v[6:7], off
	v_lshl_add_u64 v[4:5], v[4:5], 0, s[94:95]
	s_add_i32 m0, s51, 0x1a000
	s_add_i32 s66, s51, 0x8000
	s_add_i32 s67, s51, 0xa000
	global_load_lds_dwordx4 v[4:5], off
	v_lshl_add_u64 v[0:1], v[0:1], 0, s[94:95]
	s_mov_b32 m0, s66
	s_add_u32 s40, s30, 0x40080
	global_load_lds_dwordx4 v[0:1], off
	v_lshl_add_u64 v[0:1], v[2:3], 0, s[94:95]
	s_mov_b32 m0, s67
	s_addc_u32 s41, s31, 0
	global_load_lds_dwordx4 v[0:1], off
	s_add_i32 m0, s51, 0x1c000
	v_lshl_add_u64 v[0:1], s[40:41], 0, v[146:147]
	global_load_lds_dwordx4 v[0:1], off
	v_lshl_add_u64 v[0:1], s[40:41], 0, v[128:129]
	s_add_i32 m0, s51, 0x1e000
	v_bfe_u32 v141, v8, 4, 2
	global_load_lds_dwordx4 v[0:1], off
	s_waitcnt vmcnt(8)
	s_barrier
	v_and_b32_e32 v140, 15, v8
	v_lshlrev_b32_e32 v0, 4, v141
	v_lshlrev_b32_e32 v1, 2, v8
	v_lshl_or_b32 v0, v140, 6, v0
	v_and_b32_e32 v1, 32, v1
	v_bitop3_b32 v2, v0, s20, v1 bitop3:0xde
	v_bitop3_b32 v142, v0, s21, v1 bitop3:0xde
	v_lshlrev_b32_e32 v0, 14, v13
	v_and_b32_e32 v0, 0xffff8000, v0
	v_lshl_add_u32 v0, v12, 11, v0
	v_and_b32_e32 v1, 1, v13
	v_lshl_or_b32 v0, v1, 6, v0
	v_lshl_add_u32 v134, v14, 1, v0
	v_lshlrev_b32_e32 v0, 14, v9
	v_and_b32_e32 v0, 0xffff8000, v0
	s_waitcnt vmcnt(6)
	v_lshl_add_u32 v0, v10, 11, v0
	v_and_b32_e32 v1, 1, v9
	s_cmpk_lt_u32 s23, 0x100
	v_lshl_or_b32 v0, v1, 6, v0
	s_sext_i32_i16 s37, s22
	s_cselect_b64 s[22:23], -1, 0
	v_mov_b32_e32 v135, v147
	v_lshl_add_u32 v136, v11, 1, v0
	v_mov_b32_e32 v137, v147
	s_mov_b32 s68, 0
	v_add_u32_e32 v143, 0, v2
	s_barrier
	s_branch .LBB0_468
